# attention tile loop: QK and PV LDS fragment reads pipelined 6-8 deep with counted lgkmcnt (on top of GLA rewrite)
# speedup vs baseline: 1.0083x; 1.0083x over previous
; #define LAS __attribute__((address_space(3)))
; __device__ __forceinline__ void phase_attn(const Frame& F, int l, bool last, int ai, int na) {
;     ...
;             const int kpos0 = wlo + t * 64, q0w = qb * 128 + (w & 3) * 32;
;             const bool win = (t < nwin) && !(kpos0 <= q0w + 65 && kpos0 >= q0w - 97);
;             if ((t < nwin) && (kpos0 > q0w + 159 || kpos0 < q0w - 191)) continue;
;             f32x16 sacc[2];
; #pragma unroll
;             for (int kt = 0; kt < 2; ++kt) {
; #pragma unroll
;                 for (int e = 0; e < 16; ++e) sacc[kt][e] = 0.f;
; #pragma unroll
;                 for (int s = 0; s < 8; ++s) { const f16x8 a = *(const LAS f16x8*)(lds + bo + AT_K + ((kt * 32 + r32) * 136 + s * 16 + hh * 8) * 2);
;                     sacc[kt] = __builtin_amdgcn_mfma_f32_32x32x16_f16(a, qf[s], sacc[kt], 0, 0, 0); } }
;             float mx = -1e30f;
; #pragma unroll
;             for (int kt = 0; kt < 2; ++kt)
; #pragma unroll
;                 for (int e = 0; e < 16; ++e) {
;                     if (win) { const int kp = kpos0 + kt * 32 + (e & 3) + 8 * (e >> 2) + 4 * hh; const int dd = kp - qpos; if (dd > 128 || dd < -128) sacc[kt][e] = -1e30f; }
;                     mx = fmaxf(mx, sacc[kt][e]); }
;             mx = fmaxf(mx, __shfl_xor(mx, 32));
.LBB0_614:
	s_andn2_b64 vcc, exec, s[10:11]
	s_cbranch_vccnz .LBB0_618
	s_cmp_gt_i32 s41, s34
	s_cselect_b64 s[10:11], -1, 0
	s_cmp_lt_i32 s41, s35
	s_cselect_b64 s[42:43], -1, 0
	s_or_b64 s[10:11], s[10:11], s[42:43]
	s_and_b64 s[10:11], s[2:3], s[10:11]
	s_add_i32 s2, s40, 0
	v_add_u32_e32 v14, s2, v189
	v_add_u32_e32 v15, s2, v190
	s_mov_b32 s3, 0xf149f2ca
	ds_read_b128 v[2:5], v14
	ds_read_b128 v[6:9], v15
	ds_read_b128 v[10:13], v14 offset:32
	ds_read_b128 v[200:203], v15 offset:32
	ds_read_b128 v[242:245], v14 offset:64
	ds_read_b128 v[246:249], v15 offset:64
	s_waitcnt lgkmcnt(5)
	v_mfma_f32_32x32x16_f16 v[96:111], v[2:5], v[112:115], 0
	ds_read_b128 v[2:5], v14 offset:96
	s_waitcnt lgkmcnt(5)
	v_mfma_f32_32x32x16_f16 v[80:95], v[6:9], v[112:115], 0
	ds_read_b128 v[6:9], v15 offset:96
	s_waitcnt lgkmcnt(5)
	v_mfma_f32_32x32x16_f16 v[96:111], v[10:13], v[116:119], v[96:111]
	ds_read_b128 v[10:13], v14 offset:128
	s_waitcnt lgkmcnt(5)
	v_mfma_f32_32x32x16_f16 v[80:95], v[200:203], v[116:119], v[80:95]
	ds_read_b128 v[200:203], v15 offset:128
	s_waitcnt lgkmcnt(5)
	v_mfma_f32_32x32x16_f16 v[96:111], v[242:245], v[120:123], v[96:111]
	ds_read_b128 v[242:245], v14 offset:160
	s_waitcnt lgkmcnt(5)
	v_mfma_f32_32x32x16_f16 v[80:95], v[246:249], v[120:123], v[80:95]
	ds_read_b128 v[246:249], v15 offset:160
	s_waitcnt lgkmcnt(5)
	v_mfma_f32_32x32x16_f16 v[96:111], v[2:5], v[124:127], v[96:111]
	ds_read_b128 v[2:5], v14 offset:192
	s_waitcnt lgkmcnt(5)
	v_mfma_f32_32x32x16_f16 v[80:95], v[6:9], v[124:127], v[80:95]
	ds_read_b128 v[6:9], v15 offset:192
	s_waitcnt lgkmcnt(5)
	v_mfma_f32_32x32x16_f16 v[96:111], v[10:13], v[128:131], v[96:111]
	ds_read_b128 v[10:13], v14 offset:224
	s_waitcnt lgkmcnt(5)
	v_mfma_f32_32x32x16_f16 v[80:95], v[200:203], v[128:131], v[80:95]
	ds_read_b128 v[200:203], v15 offset:224
	s_waitcnt lgkmcnt(5)
	v_mfma_f32_32x32x16_f16 v[96:111], v[242:245], v[132:135], v[96:111]
	s_waitcnt lgkmcnt(4)
	v_mfma_f32_32x32x16_f16 v[80:95], v[246:249], v[132:135], v[80:95]
	s_waitcnt lgkmcnt(3)
	v_mfma_f32_32x32x16_f16 v[96:111], v[2:5], v[136:139], v[96:111]
	s_waitcnt lgkmcnt(2)
	v_mfma_f32_32x32x16_f16 v[80:95], v[6:9], v[136:139], v[80:95]
	s_waitcnt lgkmcnt(1)
	v_mfma_f32_32x32x16_f16 v[96:111], v[10:13], v[140:143], v[96:111]
	s_waitcnt lgkmcnt(0)
	v_mfma_f32_32x32x16_f16 v[80:95], v[200:203], v[140:143], v[80:95]
	v_add_u32_e32 v0, s38, v229
	v_add_u32_e32 v6, 0xffffff82, v0
	v_add_u32_e32 v7, 0xffffff87, v0
	v_add_u32_e32 v8, 0xffffff88, v0
	v_add_u32_e32 v9, 0xffffff89, v0
	v_add_u32_e32 v10, 0xffffff8a, v0
	s_nop 3
	v_add_u32_e32 v2, 0xffffff7f, v0
	v_cmp_gt_u32_e32 vcc, s83, v2
	s_and_b64 vcc, s[10:11], vcc
	v_add_u32_e32 v3, 0xffffff80, v0
	v_cndmask_b32_e32 v2, v96, v241, vcc
	v_cmp_gt_u32_e32 vcc, s83, v3
	s_and_b64 vcc, s[10:11], vcc
	v_add_u32_e32 v5, 0xffffff81, v0
	v_cndmask_b32_e32 v3, v97, v241, vcc
	v_cmp_gt_u32_e32 vcc, s83, v5
	s_and_b64 vcc, s[10:11], vcc
	v_add_u32_e32 v11, 0xffffff8f, v0
	v_cndmask_b32_e32 v5, v98, v241, vcc
	v_cmp_gt_u32_e32 vcc, s83, v6
	s_and_b64 vcc, s[10:11], vcc
	v_add_u32_e32 v12, 0xffffff90, v0
	v_cndmask_b32_e32 v6, v99, v241, vcc
	v_cmp_gt_u32_e32 vcc, s83, v7
	s_and_b64 vcc, s[10:11], vcc
	v_add_u32_e32 v13, 0xffffff91, v0
	v_cndmask_b32_e32 v7, v100, v241, vcc
	v_cmp_gt_u32_e32 vcc, s83, v8
	s_and_b64 vcc, s[10:11], vcc
	v_add_u32_e32 v14, 0xffffff92, v0
	v_cndmask_b32_e32 v8, v101, v241, vcc
	v_cmp_gt_u32_e32 vcc, s83, v9
	s_and_b64 vcc, s[10:11], vcc
	v_add_u32_e32 v15, 0xffffff97, v0
	v_cndmask_b32_e32 v9, v102, v241, vcc
	v_cmp_gt_u32_e32 vcc, s83, v10
	s_and_b64 vcc, s[10:11], vcc
	v_add_u32_e32 v96, 0xffffff98, v0
	v_cndmask_b32_e32 v10, v103, v241, vcc
	v_cmp_gt_u32_e32 vcc, s83, v11
	s_and_b64 vcc, s[10:11], vcc
	v_add_u32_e32 v97, 0xffffff99, v0
	v_cndmask_b32_e32 v11, v104, v241, vcc
	v_cmp_gt_u32_e32 vcc, s83, v12
	s_and_b64 vcc, s[10:11], vcc
	v_add_u32_e32 v98, 0xffffff9a, v0
	v_cndmask_b32_e32 v12, v105, v241, vcc
	v_cmp_gt_u32_e32 vcc, s83, v13
	s_and_b64 vcc, s[10:11], vcc
	v_add_u32_e32 v99, 0xffffff9f, v0
	v_cndmask_b32_e32 v13, v106, v241, vcc
	v_cmp_gt_u32_e32 vcc, s83, v14
	s_and_b64 vcc, s[10:11], vcc
	v_max3_f32 v4, v2, s3, v3
	v_cndmask_b32_e32 v14, v107, v241, vcc
	v_cmp_gt_u32_e32 vcc, s83, v15
	s_and_b64 vcc, s[10:11], vcc
	v_max3_f32 v4, v4, v5, v6
	v_cndmask_b32_e32 v15, v108, v241, vcc
	v_cmp_gt_u32_e32 vcc, s83, v96
	s_and_b64 vcc, s[10:11], vcc
	v_max3_f32 v4, v4, v7, v8
	v_cndmask_b32_e32 v96, v109, v241, vcc
	v_cmp_gt_u32_e32 vcc, s83, v97
	s_and_b64 vcc, s[10:11], vcc
	v_max3_f32 v4, v4, v9, v10
	v_cndmask_b32_e32 v97, v110, v241, vcc
	v_cmp_gt_u32_e32 vcc, s83, v98
	s_and_b64 vcc, s[10:11], vcc
	v_max3_f32 v4, v4, v11, v12
	v_cndmask_b32_e32 v98, v111, v241, vcc
	v_cmp_gt_u32_e32 vcc, s83, v99
	s_and_b64 vcc, s[10:11], vcc
	v_add_u32_e32 v99, 0xffffffa0, v0
	v_cndmask_b32_e32 v80, v80, v241, vcc
	v_cmp_gt_u32_e32 vcc, s83, v99
	s_and_b64 vcc, s[10:11], vcc
	v_add_u32_e32 v99, 0xffffffa1, v0
	v_cndmask_b32_e32 v81, v81, v241, vcc
	v_cmp_gt_u32_e32 vcc, s83, v99
	s_and_b64 vcc, s[10:11], vcc
	v_add_u32_e32 v99, 0xffffffa2, v0
	v_cndmask_b32_e32 v82, v82, v241, vcc
	v_cmp_gt_u32_e32 vcc, s83, v99
	s_and_b64 vcc, s[10:11], vcc
	v_add_u32_e32 v99, 0xffffffa7, v0
	v_cndmask_b32_e32 v83, v83, v241, vcc
	v_cmp_gt_u32_e32 vcc, s83, v99
	s_and_b64 vcc, s[10:11], vcc
	v_add_u32_e32 v99, 0xffffffa8, v0
	v_cndmask_b32_e32 v84, v84, v241, vcc
	v_cmp_gt_u32_e32 vcc, s83, v99
	s_and_b64 vcc, s[10:11], vcc
	v_add_u32_e32 v99, 0xffffffa9, v0
	v_cndmask_b32_e32 v85, v85, v241, vcc
	v_cmp_gt_u32_e32 vcc, s83, v99
	s_and_b64 vcc, s[10:11], vcc
; #define LAS __attribute__((address_space(3)))
; __device__ __forceinline__ void phase_attn(const Frame& F, int l, bool last, int ai, int na) {
;     ...
;             float mx = -1e30f;
; #pragma unroll
;             for (int kt = 0; kt < 2; ++kt)
; #pragma unroll
;                 for (int e = 0; e < 16; ++e) {
;                     if (win) { const int kp = kpos0 + kt * 32 + (e & 3) + 8 * (e >> 2) + 4 * hh; const int dd = kp - qpos; if (dd > 128 || dd < -128) sacc[kt][e] = -1e30f; }
;                     mx = fmaxf(mx, sacc[kt][e]); }
;             mx = fmaxf(mx, __shfl_xor(mx, 32));
;             const bool upd = mx > mrun + 8.0f;
;             const bool anyupd = __builtin_amdgcn_ballot_w64(upd) != 0ull;
;             const float mnew = upd ? mx : mrun;
;             float rs = 0.f;
; #pragma unroll
;             for (int kt = 0; kt < 2; ++kt)
; #pragma unroll
;                 for (int g4 = 0; g4 < 4; ++g4) { float pv4[4];
; #pragma unroll
;                     for (int e = 0; e < 4; ++e) { pv4[e] = __builtin_amdgcn_exp2f(sacc[kt][g4 * 4 + e] - mnew); rs += pv4[e]; }
;                     *(LAS u32x2*)(Pw + (r32 * 72 + kt * 32 + g4 * 8 + hh * 4) * 2) = (u32x2){pk_f16(pv4[0], pv4[1]), pk_f16(pv4[2], pv4[3])}; }
;             rs += __shfl_xor(rs, 32);
;             if (anyupd) { const float alpha = __builtin_amdgcn_exp2f(mrun - mnew); lrun *= alpha;
; #pragma unroll
;                 for (int dt = 0; dt < 4; ++dt)
; #pragma unroll
;                     for (int e = 0; e < 16; ++e) oacc[dt][e] *= alpha; }
;             lrun += rs; mrun = mnew;
	v_add_u32_e32 v99, 0xffffffaa, v0
	v_cndmask_b32_e32 v86, v86, v241, vcc
	v_cmp_gt_u32_e32 vcc, s83, v99
	s_and_b64 vcc, s[10:11], vcc
	v_add_u32_e32 v99, 0xffffffaf, v0
	v_cndmask_b32_e32 v87, v87, v241, vcc
	v_cmp_gt_u32_e32 vcc, s83, v99
	s_and_b64 vcc, s[10:11], vcc
	v_add_u32_e32 v99, 0xffffffb0, v0
	v_cndmask_b32_e32 v88, v88, v241, vcc
	v_cmp_gt_u32_e32 vcc, s83, v99
	s_and_b64 vcc, s[10:11], vcc
	v_add_u32_e32 v99, 0xffffffb1, v0
	v_cndmask_b32_e32 v89, v89, v241, vcc
	v_cmp_gt_u32_e32 vcc, s83, v99
	s_and_b64 vcc, s[10:11], vcc
	v_add_u32_e32 v99, 0xffffffb2, v0
	v_cndmask_b32_e32 v90, v90, v241, vcc
	v_cmp_gt_u32_e32 vcc, s83, v99
	v_max3_f32 v4, v4, v13, v14
	s_and_b64 vcc, s[10:11], vcc
	v_add_u32_e32 v99, 0xffffffb7, v0
	v_max3_f32 v4, v4, v15, v96
	v_cndmask_b32_e32 v91, v91, v241, vcc
	v_cmp_gt_u32_e32 vcc, s83, v99
	v_max3_f32 v4, v4, v97, v98
	s_and_b64 vcc, s[10:11], vcc
	v_add_u32_e32 v99, 0xffffffb8, v0
	v_max3_f32 v4, v4, v80, v81
	v_cndmask_b32_e32 v92, v92, v241, vcc
	v_cmp_gt_u32_e32 vcc, s83, v99
	v_max3_f32 v4, v4, v82, v83
	s_and_b64 vcc, s[10:11], vcc
	v_add_u32_e32 v99, 0xffffffb9, v0
	v_max3_f32 v4, v4, v84, v85
	v_cndmask_b32_e32 v93, v93, v241, vcc
	v_cmp_gt_u32_e32 vcc, s83, v99
	v_max3_f32 v4, v4, v86, v87
	s_and_b64 vcc, s[10:11], vcc
	v_add_u32_e32 v0, 0xffffffba, v0
	v_max3_f32 v4, v4, v88, v89
	v_cndmask_b32_e32 v94, v94, v241, vcc
	v_cmp_gt_u32_e32 vcc, s83, v0
	v_max3_f32 v4, v4, v90, v91
	s_and_b64 vcc, s[10:11], vcc
	v_max3_f32 v4, v4, v92, v93
	v_cndmask_b32_e32 v95, v95, v241, vcc
	v_and_b32_e32 v99, 64, v237
	v_max3_f32 v0, v4, v94, v95
	v_xor_b32_e32 v4, 32, v237
	v_add_u32_e32 v99, 64, v99
	v_cmp_lt_i32_e32 vcc, v4, v99
	s_nop 1
	v_cndmask_b32_e32 v4, v237, v4, vcc
	v_lshlrev_b32_e32 v99, 2, v4
	ds_bpermute_b32 v4, v99, v0
	s_waitcnt lgkmcnt(0)
	v_max_f32_e32 v4, v4, v4
	v_max_f32_e32 v0, v0, v4
	v_add_f32_e32 v4, 0x41000000, v230
	v_cmp_gt_f32_e32 vcc, v0, v4
	s_nop 1
	v_cndmask_b32_e32 v0, v230, v0, vcc
	v_sub_f32_e32 v2, v2, v0
	v_exp_f32_e32 v2, v2
	v_sub_f32_e32 v3, v3, v0
	v_exp_f32_e32 v3, v3
	v_sub_f32_e32 v5, v5, v0
	v_sub_f32_e32 v6, v6, v0
	v_exp_f32_e32 v5, v5
	v_exp_f32_e32 v6, v6
	v_add_f32_e32 v4, 0, v2
	v_add_f32_e32 v4, v3, v4
	v_add_f32_e32 v4, v5, v4
	v_cvt_pk_f16_f32 v2, v2, v3
	v_cvt_pk_f16_f32 v3, v5, v6
	v_sub_f32_e32 v5, v7, v0
	v_add_f32_e32 v4, v6, v4
	v_exp_f32_e32 v5, v5
	v_sub_f32_e32 v6, v8, v0
	v_exp_f32_e32 v6, v6
	v_sub_f32_e32 v7, v9, v0
	v_exp_f32_e32 v7, v7
	v_sub_f32_e32 v8, v10, v0
	v_exp_f32_e32 v8, v8
	v_add_f32_e32 v4, v5, v4
	v_add_f32_e32 v4, v6, v4
	v_add_f32_e32 v4, v7, v4
	v_add_f32_e32 v9, v8, v4
	v_cvt_pk_f16_f32 v4, v5, v6
	v_cvt_pk_f16_f32 v5, v7, v8
	ds_write2_b64 v228, v[2:3], v[4:5] offset1:2
	v_sub_f32_e32 v2, v11, v0
	v_exp_f32_e32 v2, v2
	v_sub_f32_e32 v4, v12, v0
	v_exp_f32_e32 v4, v4
	v_sub_f32_e32 v5, v13, v0
	v_add_f32_e32 v3, v2, v9
	v_exp_f32_e32 v5, v5
	v_sub_f32_e32 v6, v14, v0
	v_add_f32_e32 v3, v4, v3
	v_exp_f32_e32 v6, v6
	v_cvt_pk_f16_f32 v2, v2, v4
	v_sub_f32_e32 v4, v15, v0
	v_exp_f32_e32 v4, v4
	v_add_f32_e32 v3, v5, v3
	v_add_f32_e32 v7, v6, v3
	v_cvt_pk_f16_f32 v3, v5, v6
	v_sub_f32_e32 v6, v96, v0
	v_add_f32_e32 v5, v4, v7
	v_exp_f32_e32 v6, v6
	v_sub_f32_e32 v7, v97, v0
	v_exp_f32_e32 v7, v7
	v_sub_f32_e32 v8, v98, v0
	v_exp_f32_e32 v8, v8
	v_add_f32_e32 v5, v6, v5
	v_add_f32_e32 v5, v7, v5
	v_cvt_pk_f16_f32 v4, v4, v6
	v_add_f32_e32 v9, v8, v5
	v_cvt_pk_f16_f32 v5, v7, v8
	ds_write2_b64 v228, v[2:3], v[4:5] offset0:4 offset1:6
	v_sub_f32_e32 v2, v80, v0
	v_exp_f32_e32 v2, v2
	v_sub_f32_e32 v4, v81, v0
	v_exp_f32_e32 v4, v4
	v_sub_f32_e32 v5, v82, v0
	v_add_f32_e32 v3, v2, v9
	v_exp_f32_e32 v5, v5
	v_sub_f32_e32 v6, v83, v0
	v_add_f32_e32 v3, v4, v3
	v_exp_f32_e32 v6, v6
	v_cvt_pk_f16_f32 v2, v2, v4
	v_sub_f32_e32 v4, v84, v0
	v_exp_f32_e32 v4, v4
	v_add_f32_e32 v3, v5, v3
	v_add_f32_e32 v7, v6, v3
	v_cvt_pk_f16_f32 v3, v5, v6
	v_sub_f32_e32 v6, v85, v0
	v_add_f32_e32 v5, v4, v7
	v_exp_f32_e32 v6, v6
	v_sub_f32_e32 v7, v86, v0
	v_exp_f32_e32 v7, v7
	v_sub_f32_e32 v8, v87, v0
	v_exp_f32_e32 v8, v8
	v_add_f32_e32 v5, v6, v5
	v_add_f32_e32 v5, v7, v5
	v_cvt_pk_f16_f32 v4, v4, v6
	v_add_f32_e32 v9, v8, v5
	v_cvt_pk_f16_f32 v5, v7, v8
	ds_write2_b64 v228, v[2:3], v[4:5] offset0:8 offset1:10
	v_sub_f32_e32 v2, v88, v0
	v_exp_f32_e32 v2, v2
	v_sub_f32_e32 v4, v89, v0
	v_exp_f32_e32 v4, v4
	v_sub_f32_e32 v5, v90, v0
	v_exp_f32_e32 v5, v5
	v_sub_f32_e32 v6, v91, v0
	v_exp_f32_e32 v6, v6
	v_add_f32_e32 v3, v2, v9
	v_add_f32_e32 v3, v4, v3
	v_add_f32_e32 v3, v5, v3
	v_cvt_pk_f16_f32 v4, v2, v4
	v_sub_f32_e32 v2, v92, v0
	v_add_f32_e32 v3, v6, v3
	v_cvt_pk_f16_f32 v5, v5, v6
	v_exp_f32_e32 v6, v2
	v_sub_f32_e32 v7, v94, v0
	v_exp_f32_e32 v7, v7
	v_sub_f32_e32 v8, v95, v0
	v_add_f32_e32 v2, v6, v3
	v_sub_f32_e32 v3, v93, v0
	v_exp_f32_e32 v3, v3
	v_exp_f32_e32 v8, v8
	v_add_f32_e32 v2, v3, v2
	v_add_f32_e32 v2, v7, v2
	v_add_f32_e32 v2, v8, v2
	v_cvt_pk_f16_f32 v6, v6, v3
	ds_bpermute_b32 v3, v99, v2
	v_cvt_pk_f16_f32 v7, v7, v8
	ds_write2_b64 v228, v[4:5], v[6:7] offset0:12 offset1:14
	s_cbranch_vccz .LBB0_617
	v_sub_f32_e32 v4, v230, v0
	v_exp_f32_e32 v4, v4
	s_nop 0
	v_pk_mul_f32 v[78:79], v[78:79], v[4:5] op_sel_hi:[1,0]
	v_pk_mul_f32 v[76:77], v[76:77], v[4:5] op_sel_hi:[1,0]
	v_pk_mul_f32 v[74:75], v[74:75], v[4:5] op_sel_hi:[1,0]
	v_pk_mul_f32 v[72:73], v[72:73], v[4:5] op_sel_hi:[1,0]
	v_pk_mul_f32 v[70:71], v[70:71], v[4:5] op_sel_hi:[1,0]
	v_pk_mul_f32 v[68:69], v[68:69], v[4:5] op_sel_hi:[1,0]
	v_pk_mul_f32 v[66:67], v[66:67], v[4:5] op_sel_hi:[1,0]
	v_pk_mul_f32 v[64:65], v[64:65], v[4:5] op_sel_hi:[1,0]
	v_pk_mul_f32 v[62:63], v[62:63], v[4:5] op_sel_hi:[1,0]
	v_pk_mul_f32 v[60:61], v[60:61], v[4:5] op_sel_hi:[1,0]
	v_pk_mul_f32 v[58:59], v[58:59], v[4:5] op_sel_hi:[1,0]
	v_pk_mul_f32 v[56:57], v[56:57], v[4:5] op_sel_hi:[1,0]
	v_pk_mul_f32 v[54:55], v[54:55], v[4:5] op_sel_hi:[1,0]
	v_pk_mul_f32 v[52:53], v[52:53], v[4:5] op_sel_hi:[1,0]
	v_pk_mul_f32 v[50:51], v[50:51], v[4:5] op_sel_hi:[1,0]
	v_pk_mul_f32 v[48:49], v[48:49], v[4:5] op_sel_hi:[1,0]
	v_pk_mul_f32 v[46:47], v[46:47], v[4:5] op_sel_hi:[1,0]
	v_pk_mul_f32 v[44:45], v[44:45], v[4:5] op_sel_hi:[1,0]
	v_pk_mul_f32 v[42:43], v[42:43], v[4:5] op_sel_hi:[1,0]
	v_pk_mul_f32 v[40:41], v[40:41], v[4:5] op_sel_hi:[1,0]
	v_pk_mul_f32 v[38:39], v[38:39], v[4:5] op_sel_hi:[1,0]
	v_pk_mul_f32 v[36:37], v[36:37], v[4:5] op_sel_hi:[1,0]
	v_pk_mul_f32 v[34:35], v[34:35], v[4:5] op_sel_hi:[1,0]
	v_pk_mul_f32 v[32:33], v[32:33], v[4:5] op_sel_hi:[1,0]
	v_pk_mul_f32 v[30:31], v[30:31], v[4:5] op_sel_hi:[1,0]
	v_pk_mul_f32 v[28:29], v[28:29], v[4:5] op_sel_hi:[1,0]
	v_pk_mul_f32 v[26:27], v[26:27], v[4:5] op_sel_hi:[1,0]
	v_pk_mul_f32 v[24:25], v[24:25], v[4:5] op_sel_hi:[1,0]
	v_pk_mul_f32 v[22:23], v[22:23], v[4:5] op_sel_hi:[1,0]
	v_pk_mul_f32 v[20:21], v[20:21], v[4:5] op_sel_hi:[1,0]
	v_pk_mul_f32 v[18:19], v[18:19], v[4:5] op_sel_hi:[1,0]
	v_pk_mul_f32 v[16:17], v[16:17], v[4:5] op_sel_hi:[1,0]
	v_mul_f32_e32 v171, v171, v4
; #define LAS __attribute__((address_space(3)))
; __device__ __forceinline__ void phase_attn(const Frame& F, int l, bool last, int ai, int na) {
;     ...
;             lrun += rs; mrun = mnew;
;             asm volatile("s_waitcnt lgkmcnt(0)" ::: "memory");
; #pragma unroll
;             for (int s = 0; s < 4; ++s) { const f16x8 pb = *(const LAS f16x8*)(Pw + (r32 * 72 + s * 16 + hh * 8) * 2);
; #pragma unroll
;                 for (int dt = 0; dt < 4; ++dt) { const f16x8 a = *(const LAS f16x8*)(lds + bo + AT_V + ((dt * 32 + r32) * 72 + s * 16 + hh * 8) * 2);
;                     oacc[dt] = __builtin_amdgcn_mfma_f32_32x32x16_f16(a, pb, oacc[dt], 0, 0, 0); } }
;         }
.LBB0_617:
	v_add_u32_e32 v12, s12, v191
	ds_read_b128 v[200:203], v12
	ds_read_b128 v[242:245], v12 offset:32
	ds_read_b128 v[246:249], v12 offset:64
	ds_read_b128 v[8:11], v12 offset:96
	v_add_u32_e32 v4, s2, v191
	ds_read_b128 v[80:83], v4 offset:17408
	v_add_u32_e32 v5, s2, v192
	ds_read_b128 v[84:87], v5 offset:17408
	v_add_u32_e32 v6, s2, v193
	ds_read_b128 v[88:91], v6 offset:17408
	v_add_u32_e32 v7, s2, v194
	ds_read_b128 v[92:95], v7 offset:17408
	v_add_u32_e32 v13, s2, v195
	ds_read_b128 v[96:99], v13 offset:17408
	v_add_u32_e32 v14, s2, v214
	ds_read_b128 v[100:103], v14 offset:17408
	v_add_u32_e32 v15, s2, v215
	ds_read_b128 v[104:107], v15 offset:17408
	v_add_u32_e32 v4, s2, v216
	ds_read_b128 v[108:111], v4 offset:17408
	s_waitcnt lgkmcnt(12)
	v_add_f32_e32 v2, v2, v3
	v_add_f32_e32 v171, v2, v171
	s_waitcnt lgkmcnt(7)
	v_mfma_f32_32x32x16_f16 v[64:79], v[80:83], v[200:203], v[64:79]
	v_add_u32_e32 v5, s2, v217
	ds_read_b128 v[80:83], v5 offset:17408
	s_waitcnt lgkmcnt(7)
	v_mfma_f32_32x32x16_f16 v[48:63], v[84:87], v[200:203], v[48:63]
	v_add_u32_e32 v6, s2, v218
	ds_read_b128 v[84:87], v6 offset:17408
	s_waitcnt lgkmcnt(7)
	v_mfma_f32_32x32x16_f16 v[32:47], v[88:91], v[200:203], v[32:47]
	v_add_u32_e32 v7, s2, v219
	ds_read_b128 v[88:91], v7 offset:17408
	s_waitcnt lgkmcnt(7)
	v_mfma_f32_32x32x16_f16 v[16:31], v[92:95], v[200:203], v[16:31]
	v_add_u32_e32 v13, s2, v220
	ds_read_b128 v[92:95], v13 offset:17408
	s_waitcnt lgkmcnt(7)
	v_mfma_f32_32x32x16_f16 v[64:79], v[96:99], v[242:245], v[64:79]
	v_add_u32_e32 v14, s2, v221
	ds_read_b128 v[96:99], v14 offset:17408
	s_waitcnt lgkmcnt(7)
	v_mfma_f32_32x32x16_f16 v[48:63], v[100:103], v[242:245], v[48:63]
	v_add_u32_e32 v15, s2, v222
	ds_read_b128 v[100:103], v15 offset:17408
	s_waitcnt lgkmcnt(7)
	v_mfma_f32_32x32x16_f16 v[32:47], v[104:107], v[242:245], v[32:47]
	v_add_u32_e32 v4, s2, v223
	ds_read_b128 v[104:107], v4 offset:17408
	s_waitcnt lgkmcnt(7)
	v_mfma_f32_32x32x16_f16 v[16:31], v[108:111], v[242:245], v[16:31]
	v_add_u32_e32 v5, s2, v224
	ds_read_b128 v[108:111], v5 offset:17408
	s_waitcnt lgkmcnt(7)
	v_mfma_f32_32x32x16_f16 v[64:79], v[80:83], v[246:249], v[64:79]
	s_waitcnt lgkmcnt(6)
	v_mfma_f32_32x32x16_f16 v[48:63], v[84:87], v[246:249], v[48:63]
	s_waitcnt lgkmcnt(5)
	v_mfma_f32_32x32x16_f16 v[32:47], v[88:91], v[246:249], v[32:47]
	s_waitcnt lgkmcnt(4)
	v_mfma_f32_32x32x16_f16 v[16:31], v[92:95], v[246:249], v[16:31]
	s_waitcnt lgkmcnt(3)
	v_mfma_f32_32x32x16_f16 v[64:79], v[96:99], v[8:11], v[64:79]
	s_waitcnt lgkmcnt(2)
	v_mfma_f32_32x32x16_f16 v[48:63], v[100:103], v[8:11], v[48:63]
	s_waitcnt lgkmcnt(1)
	v_mfma_f32_32x32x16_f16 v[32:47], v[104:107], v[8:11], v[32:47]
	s_waitcnt lgkmcnt(0)
	v_mfma_f32_32x32x16_f16 v[16:31], v[108:111], v[8:11], v[16:31]
	s_add_i32 s38, s38, 64
	s_add_i32 s39, s39, 1
	s_cmp_eq_u32 s28, s39
	s_cbranch_scc0 .LBB0_619
	s_branch .LBB0_602
